# attention: V^T fragment reads issued right after the bias reads (ctx path: in place of the nop), bias wait leaves them in flight
# speedup vs baseline: 1.0069x; 1.0004x over previous
; __device__ __forceinline__ unsigned f2bf(float f) { unsigned u = __builtin_bit_cast(unsigned, f); return (u + 0x7fffu + ((u >> 16) & 1u)) >> 16; }
; __device__ __forceinline__ void phase_na_attn(const Fr& F) {
;     ...
;                         for (int ds = 0; ds < 2; ++ds) { const bf16x8 Kf = *(const bf16x8*)(Kl + (koff + 16 * st + l15) * KST + 32 * ds + 8 * lq);
;                             Sx[st] = __builtin_amdgcn_mfma_f32_16x16x32_bf16(Kf, Qf[ds], Sx[st], 0, 0, 0); } }
;                     float pv[2][4];
; #pragma unroll
;                     for (int st = 0; st < 2; ++st)
; #pragma unroll
;                         for (int reg = 0; reg < 4; ++reg) {
;                             if (nb) { const int bo = boff[st][reg]; pv[st][reg] = bo >= 0 ? __expf(Sx[st][reg] + rpbT[(rr - gi + 7) * 31 + bo]) : 0.f; }
;                             else pv[st][reg] = __expf(Sx[st][reg]); }
;                     u32x4 pw; pw.x = f2bf(pv[0][0]) | (f2bf(pv[0][1]) << 16); pw.y = f2bf(pv[0][2]) | (f2bf(pv[0][3]) << 16); pw.z = f2bf(pv[1][0]) | (f2bf(pv[1][1]) << 16); pw.w = f2bf(pv[1][2]) | (f2bf(pv[1][3]) << 16);
;                     lsum += ((lo_bf(pw.x) + hi_bf(pw.x)) + (lo_bf(pw.y) + hi_bf(pw.y))) + ((lo_bf(pw.z) + hi_bf(pw.z)) + (lo_bf(pw.w) + hi_bf(pw.w)));
;                     const bf16x8 Pb = __builtin_bit_cast(bf16x8, pw);
; #pragma unroll
;                     for (int dt = 0; dt < 4; ++dt) { const bf16* vp = Vl + (16 * dt + l15) * KST + koff + 4 * lq;
;                         u32x4 vw; const u32x2 v0 = *(const u32x2*)vp, v1 = *(const u32x2*)(vp + 16); vw.x = v0.x; vw.y = v0.y; vw.z = v1.x; vw.w = v1.y;
.LBB0_1087:
	s_and_b64 s[24:25], s[54:55], exec
	s_cselect_b32 s86, s75, s85
	v_add_u32_e32 v48, s86, v61
	v_mad_u64_u32 v[108:109], s[24:25], v48, s73, v[66:67]
	ds_read_b128 v[48:51], v108
	ds_read_b128 v[52:55], v108 offset:64
	ds_read_b128 v[104:107], v108 offset:2304
	ds_read_b128 v[108:111], v108 offset:2368
	s_mov_b64 s[24:25], -1
	s_waitcnt lgkmcnt(3)
	v_mfma_f32_16x16x32_bf16 v[48:51], v[48:51], v[28:31], 0
	s_and_b64 vcc, exec, s[56:57]
	s_waitcnt lgkmcnt(1)
	v_mfma_f32_16x16x32_bf16 v[104:107], v[104:107], v[28:31], 0
	v_mfma_f32_16x16x32_bf16 v[52:55], v[52:55], v[24:27], v[48:51]
	s_waitcnt lgkmcnt(0)
	v_mfma_f32_16x16x32_bf16 v[48:51], v[108:111], v[24:27], v[104:107]
	s_cbranch_vccnz .Lattn_ctx1
	ds_read_b32 v112, v95 offset:50020
	ds_read_b32 v113, v96 offset:50020
	ds_read_b32 v114, v97 offset:50020
	ds_read_b32 v115, v98 offset:50020
	ds_read_b32 v116, v99 offset:50020
	ds_read_b32 v117, v100 offset:50020
	ds_read_b32 v118, v101 offset:50020
	ds_read_b32 v119, v102 offset:50020
	v_lshl_add_u32 v124, s86, 1, v82
	v_add_u32_e32 v120, 0x2000, v124
	v_add_u32_e32 v121, 0x2800, v124
	v_add_u32_e32 v122, 0x3000, v124
	v_add_u32_e32 v123, 0x3800, v124
	ds_read2_b64 v[136:139], v120 offset0:128 offset1:132
	ds_read2_b64 v[140:143], v121 offset0:160 offset1:164
	ds_read2_b64 v[144:147], v122 offset0:192 offset1:196
	ds_read2_b64 v[148:151], v123 offset0:224 offset1:228
	s_waitcnt lgkmcnt(4)
	v_add_f32_e32 v112, v52, v112
	v_add_f32_e32 v113, v53, v113
	v_add_f32_e32 v114, v54, v114
	v_add_f32_e32 v115, v55, v115
	v_add_f32_e32 v116, v48, v116
	v_add_f32_e32 v117, v49, v117
	v_add_f32_e32 v118, v50, v118
	v_add_f32_e32 v119, v51, v119
	v_mul_f32_e32 v112, 0x3fb8aa3b, v112
	v_mul_f32_e32 v113, 0x3fb8aa3b, v113
	v_mul_f32_e32 v114, 0x3fb8aa3b, v114
	v_mul_f32_e32 v115, 0x3fb8aa3b, v115
	v_mul_f32_e32 v116, 0x3fb8aa3b, v116
	v_mul_f32_e32 v117, 0x3fb8aa3b, v117
	v_mul_f32_e32 v118, 0x3fb8aa3b, v118
	v_mul_f32_e32 v119, 0x3fb8aa3b, v119
	v_exp_f32_e32 v112, v112
	v_exp_f32_e32 v113, v113
	v_exp_f32_e32 v114, v114
	v_exp_f32_e32 v115, v115
	v_exp_f32_e32 v116, v116
	v_exp_f32_e32 v117, v117
	v_exp_f32_e32 v118, v118
	v_exp_f32_e32 v119, v119
	v_cndmask_b32_e64 v103, 0, v112, s[8:9]
	v_cndmask_b32_e64 v52, 0, v113, s[10:11]
	v_cndmask_b32_e64 v53, 0, v114, s[12:13]
	v_cndmask_b32_e64 v54, 0, v115, s[14:15]
	v_cndmask_b32_e64 v55, 0, v116, s[16:17]
	v_cndmask_b32_e64 v48, 0, v117, s[18:19]
	v_cndmask_b32_e64 v49, 0, v118, s[20:21]
	v_cndmask_b32_e64 v50, 0, v119, s[22:23]
	s_branch .LBB0_1086
.Lattn_ctx1:
	v_lshl_add_u32 v124, s86, 1, v82
	v_add_u32_e32 v120, 0x2000, v124
	v_add_u32_e32 v121, 0x2800, v124
	v_add_u32_e32 v122, 0x3000, v124
	v_add_u32_e32 v123, 0x3800, v124
	ds_read2_b64 v[136:139], v120 offset0:128 offset1:132
	ds_read2_b64 v[140:143], v121 offset0:160 offset1:164
	ds_read2_b64 v[144:147], v122 offset0:192 offset1:196
	ds_read2_b64 v[148:151], v123 offset0:224 offset1:228
	v_mul_f32_e32 v103, 0x3fb8aa3b, v52
	v_mul_f32_e32 v52, 0x3fb8aa3b, v53
	v_mul_f32_e32 v53, 0x3fb8aa3b, v54
	v_mul_f32_e32 v54, 0x3fb8aa3b, v55
	v_mul_f32_e32 v55, 0x3fb8aa3b, v48
	v_mul_f32_e32 v48, 0x3fb8aa3b, v49
	v_mul_f32_e32 v49, 0x3fb8aa3b, v50
	v_mul_f32_e32 v50, 0x3fb8aa3b, v51
	v_exp_f32_e32 v103, v103
	v_exp_f32_e32 v52, v52
	v_exp_f32_e32 v53, v53
	v_exp_f32_e32 v54, v54
	v_exp_f32_e32 v55, v55
	v_exp_f32_e32 v48, v48
	v_exp_f32_e32 v49, v49
	v_exp_f32_e32 v50, v50
	s_branch .LBB0_1086

; __device__ __forceinline__ unsigned f2bf(float f) { unsigned u = __builtin_bit_cast(unsigned, f); return (u + 0x7fffu + ((u >> 16) & 1u)) >> 16; }
; __device__ __forceinline__ void phase_na_attn(const Fr& F) {
;     ...
;                         for (int ds = 0; ds < 2; ++ds) { const bf16x8 Kf = *(const bf16x8*)(Kl + (koff + 16 * st + l15) * KST + 32 * ds + 8 * lq);
;                             Sx[st] = __builtin_amdgcn_mfma_f32_16x16x32_bf16(Kf, Qf[ds], Sx[st], 0, 0, 0); } }
;                     float pv[2][4];
; #pragma unroll
;                     for (int st = 0; st < 2; ++st)
; #pragma unroll
;                         for (int reg = 0; reg < 4; ++reg) {
;                             if (nb) { const int bo = boff[st][reg]; pv[st][reg] = bo >= 0 ? __expf(Sx[st][reg] + rpbT[(rr - gi + 7) * 31 + bo]) : 0.f; }
;                             else pv[st][reg] = __expf(Sx[st][reg]); }
;                     u32x4 pw; pw.x = f2bf(pv[0][0]) | (f2bf(pv[0][1]) << 16); pw.y = f2bf(pv[0][2]) | (f2bf(pv[0][3]) << 16); pw.z = f2bf(pv[1][0]) | (f2bf(pv[1][1]) << 16); pw.w = f2bf(pv[1][2]) | (f2bf(pv[1][3]) << 16);
;                     lsum += ((lo_bf(pw.x) + hi_bf(pw.x)) + (lo_bf(pw.y) + hi_bf(pw.y))) + ((lo_bf(pw.z) + hi_bf(pw.z)) + (lo_bf(pw.w) + hi_bf(pw.w)));
;                     const bf16x8 Pb = __builtin_bit_cast(bf16x8, pw);
; #pragma unroll
;                     for (int dt = 0; dt < 4; ++dt) { const bf16* vp = Vl + (16 * dt + l15) * KST + koff + 4 * lq;
;                         u32x4 vw; const u32x2 v0 = *(const u32x2*)vp, v1 = *(const u32x2*)(vp + 16); vw.x = v0.x; vw.y = v0.y; vw.z = v1.x; vw.w = v1.y;
.LBB0_1148:
	s_and_b64 s[24:25], s[54:55], exec
	s_cselect_b32 s86, s75, s85
	v_add_u32_e32 v48, s86, v61
	v_mad_u64_u32 v[108:109], s[24:25], v48, s73, v[66:67]
	ds_read_b128 v[48:51], v108 offset:18432
	ds_read_b128 v[52:55], v108 offset:18496
	ds_read_b128 v[104:107], v108 offset:20736
	ds_read_b128 v[108:111], v108 offset:20800
	s_mov_b64 s[24:25], -1
	s_waitcnt lgkmcnt(3)
	v_mfma_f32_16x16x32_bf16 v[48:51], v[48:51], v[28:31], 0
	s_and_b64 vcc, exec, s[56:57]
	s_waitcnt lgkmcnt(1)
	v_mfma_f32_16x16x32_bf16 v[104:107], v[104:107], v[28:31], 0
	v_mfma_f32_16x16x32_bf16 v[52:55], v[52:55], v[24:27], v[48:51]
	s_waitcnt lgkmcnt(0)
	v_mfma_f32_16x16x32_bf16 v[48:51], v[108:111], v[24:27], v[104:107]
	s_cbranch_vccnz .Lattn_ctx0
	ds_read_b32 v112, v95 offset:50020
	ds_read_b32 v113, v96 offset:50020
	ds_read_b32 v114, v97 offset:50020
	ds_read_b32 v115, v98 offset:50020
	ds_read_b32 v116, v99 offset:50020
	ds_read_b32 v117, v100 offset:50020
	ds_read_b32 v118, v101 offset:50020
	ds_read_b32 v119, v102 offset:50020
	v_lshl_add_u32 v124, s86, 1, v82
	v_add_u32_e32 v120, 0x6800, v124
	v_add_u32_e32 v121, 0x7000, v124
	v_add_u32_e32 v122, 0x7800, v124
	v_add_u32_e32 v123, 0x8000, v124
	ds_read2_b64 v[136:139], v120 offset0:128 offset1:132
	ds_read2_b64 v[140:143], v121 offset0:160 offset1:164
	ds_read2_b64 v[144:147], v122 offset0:192 offset1:196
	ds_read2_b64 v[148:151], v123 offset0:224 offset1:228
	s_waitcnt lgkmcnt(4)
	v_add_f32_e32 v112, v52, v112
	v_add_f32_e32 v113, v53, v113
	v_add_f32_e32 v114, v54, v114
	v_add_f32_e32 v115, v55, v115
	v_add_f32_e32 v116, v48, v116
	v_add_f32_e32 v117, v49, v117
	v_add_f32_e32 v118, v50, v118
	v_add_f32_e32 v119, v51, v119
	v_mul_f32_e32 v112, 0x3fb8aa3b, v112
	v_mul_f32_e32 v113, 0x3fb8aa3b, v113
	v_mul_f32_e32 v114, 0x3fb8aa3b, v114
	v_mul_f32_e32 v115, 0x3fb8aa3b, v115
	v_mul_f32_e32 v116, 0x3fb8aa3b, v116
	v_mul_f32_e32 v117, 0x3fb8aa3b, v117
	v_mul_f32_e32 v118, 0x3fb8aa3b, v118
	v_mul_f32_e32 v119, 0x3fb8aa3b, v119
	v_exp_f32_e32 v112, v112
	v_exp_f32_e32 v113, v113
	v_exp_f32_e32 v114, v114
	v_exp_f32_e32 v115, v115
	v_exp_f32_e32 v116, v116
	v_exp_f32_e32 v117, v117
	v_exp_f32_e32 v118, v118
	v_exp_f32_e32 v119, v119
	v_cndmask_b32_e64 v103, 0, v112, s[8:9]
	v_cndmask_b32_e64 v52, 0, v113, s[10:11]
	v_cndmask_b32_e64 v53, 0, v114, s[12:13]
	v_cndmask_b32_e64 v54, 0, v115, s[14:15]
	v_cndmask_b32_e64 v55, 0, v116, s[16:17]
	v_cndmask_b32_e64 v48, 0, v117, s[18:19]
	v_cndmask_b32_e64 v49, 0, v118, s[20:21]
	v_cndmask_b32_e64 v50, 0, v119, s[22:23]
	s_branch .LBB0_1147
.Lattn_ctx0:
	v_lshl_add_u32 v124, s86, 1, v82
	v_add_u32_e32 v120, 0x6800, v124
	v_add_u32_e32 v121, 0x7000, v124
	v_add_u32_e32 v122, 0x7800, v124
	v_add_u32_e32 v123, 0x8000, v124
	ds_read2_b64 v[136:139], v120 offset0:128 offset1:132
	ds_read2_b64 v[140:143], v121 offset0:160 offset1:164
	ds_read2_b64 v[144:147], v122 offset0:192 offset1:196
	ds_read2_b64 v[148:151], v123 offset0:224 offset1:228
	v_mul_f32_e32 v103, 0x3fb8aa3b, v52
	v_mul_f32_e32 v52, 0x3fb8aa3b, v53
	v_mul_f32_e32 v53, 0x3fb8aa3b, v54
	v_mul_f32_e32 v54, 0x3fb8aa3b, v55
	v_mul_f32_e32 v55, 0x3fb8aa3b, v48
	v_mul_f32_e32 v48, 0x3fb8aa3b, v49
	v_mul_f32_e32 v49, 0x3fb8aa3b, v50
	v_mul_f32_e32 v50, 0x3fb8aa3b, v51
	v_exp_f32_e32 v103, v103
	v_exp_f32_e32 v52, v52
	v_exp_f32_e32 v53, v53
	v_exp_f32_e32 v54, v54
	v_exp_f32_e32 v55, v55
	v_exp_f32_e32 v48, v48
	v_exp_f32_e32 v49, v49
	v_exp_f32_e32 v50, v50
	s_branch .LBB0_1147
